# grid barrier: XCD leaders poll the cross-XCD arrival counter directly (one atomic round trip and the generation-word hop removed)
# speedup vs baseline: 1.0212x; 1.0043x over previous
.LBB0_168:
	s_andn2_saveexec_b64 s[20:21], s[20:21]
	s_cbranch_execz .LBB0_10
	v_add_u32_e32 v5, 1, v0
	v_mul_lo_u32 v5, v5, v2
	buffer_wbl2 sc1
	s_waitcnt lgkmcnt(0)
	s_waitcnt vmcnt(0)
	v_readlane_b32 s22, v254, 32
	v_readlane_b32 s23, v254, 33
	v_mov_b32_e32 v3, 1
	s_mov_b32 s6, 0
	s_nop 3
	global_atomic_add v1, v3, s[22:23]
.Lxb_spin:
	global_load_dword v4, v1, s[22:23] sc1
	s_waitcnt vmcnt(0)
	v_cmp_ge_u32_e32 vcc, v4, v5
	s_cbranch_vccnz .Lxb_go
	s_sleep 1
	s_add_i32 s6, s6, 1
	s_cmp_lt_u32 s6, 0x400000
	s_cbranch_scc1 .Lxb_spin
	v_readlane_b32 s24, v253, 50
	v_readlane_b32 s25, v253, 51
	s_nop 4
	global_atomic_add v1, v3, s[24:25]
.Lxb_go:
	v_readlane_b32 s24, v254, 30
	v_readlane_b32 s25, v254, 31
	buffer_inv sc1
	s_nop 4
	global_atomic_add v1, v3, s[24:25]
	s_waitcnt vmcnt(0)
	s_branch .LBB0_10
